# stack17 + redundant s_nop after M0 writes removed in the LDS-DMA issue snippets, single tail wait
# baseline (speedup 1.0000x reference)
.Li0_entry:
	v_add_u32_e32 v167, s79, v147
	v_add_u32_e32 v227, s79, v149
	v_add_u32_e32 v194, s79, v151
	v_add_u32_e32 v195, s79, v153
	ds_read_b128 v[64:67], v167
	ds_read_b128 v[188:191], v227
	ds_read_b128 v[228:231], v194
	s_waitcnt lgkmcnt(2)
	v_mfma_f32_32x32x16_bf16 v[64:79], v[64:67], v[80:83], 0
	s_waitcnt lgkmcnt(1)
	v_mfma_f32_32x32x16_bf16 v[64:79], v[188:191], v[84:87], v[64:79]
	ds_read_b128 v[188:191], v195
	s_mov_b64 s[54:55], 0xe404000
	s_add_i32 m0, s96, 0x8000
	v_lshl_add_u64 v[192:193], v[134:135], 0, s[54:55]
	global_load_lds_dwordx4 v[192:193], off
	v_cndmask_b32_e64 v173, v113, v121, s[2:3]
	v_cndmask_b32_e64 v172, v112, v120, s[2:3]
	v_cndmask_b32_e64 v177, v121, v113, s[2:3]
	v_cndmask_b32_e64 v176, v120, v112, s[2:3]
	s_waitcnt lgkmcnt(1)
	v_mfma_f32_32x32x16_bf16 v[64:79], v[228:231], v[88:91], v[64:79]
	ds_read_b128 v[228:231], v167 offset:128
	s_mov_b64 s[54:55], 0xe406000
	s_add_i32 m0, s96, 0xa000
	v_lshl_add_u64 v[192:193], v[134:135], 0, s[54:55]
	global_load_lds_dwordx4 v[192:193], off
	v_cndmask_b32_e64 v171, v119, v127, s[2:3]
	v_cndmask_b32_e64 v170, v118, v126, s[2:3]
	v_cndmask_b32_e64 v169, v117, v125, s[2:3]
	v_cndmask_b32_e64 v168, v116, v124, s[2:3]
	s_waitcnt lgkmcnt(1)
	v_mfma_f32_32x32x16_bf16 v[64:79], v[188:191], v[92:95], v[64:79]
	ds_read_b128 v[188:191], v227 offset:128
	s_mov_b64 s[54:55], 0xe804000
	s_add_i32 m0, s96, 0xc000
	v_lshl_add_u64 v[192:193], v[134:135], 0, s[54:55]
	global_load_lds_dwordx4 v[192:193], off
	v_cndmask_b32_e64 v175, v115, v123, s[2:3]
	v_cndmask_b32_e64 v174, v114, v122, s[2:3]
	v_cndmask_b32_e64 v127, v127, v119, s[2:3]
	v_cndmask_b32_e64 v126, v126, v118, s[2:3]
	s_waitcnt lgkmcnt(1)
	v_mfma_f32_32x32x16_bf16 v[64:79], v[228:231], v[96:99], v[64:79]
	ds_read_b128 v[228:231], v194 offset:128
	s_mov_b64 s[54:55], 0xe806000
	s_add_i32 m0, s96, 0xe000
	v_lshl_add_u64 v[192:193], v[134:135], 0, s[54:55]
	global_load_lds_dwordx4 v[192:193], off
	v_cndmask_b32_e64 v125, v125, v117, s[2:3]
	v_cndmask_b32_e64 v124, v124, v116, s[2:3]
	v_cndmask_b32_e64 v179, v123, v115, s[2:3]
	v_cndmask_b32_e64 v178, v122, v114, s[2:3]
	s_waitcnt lgkmcnt(1)
	v_mfma_f32_32x32x16_bf16 v[64:79], v[188:191], v[100:103], v[64:79]
	ds_read_b128 v[188:191], v195 offset:128
	s_cmp_gt_i32 s19, s18
	s_cbranch_scc1 .Li0_kskip
	v_lshl_add_u64 v[192:193], s[50:51], 0, v[130:131]
	s_mov_b64 s[54:55], 0xc408000
	s_mov_b32 m0, s97
	v_lshl_add_u64 v[192:193], v[192:193], 0, s[54:55]
	global_load_lds_dwordx4 v[192:193], off
	v_lshl_add_u64 v[192:193], s[50:51], 0, v[130:131]
	s_mov_b64 s[54:55], 0xc40a000
	s_mov_b32 m0, s26
	v_lshl_add_u64 v[192:193], v[192:193], 0, s[54:55]
	global_load_lds_dwordx4 v[192:193], off

.Li0_sm:
	ds_read_b64_tr_b16 v[188:189], v158 offset:0x400
	ds_read_b64_tr_b16 v[190:191], v158 offset:0xc00
	ds_read_b64_tr_b16 v[192:193], v158 offset:0x600
	ds_read_b64_tr_b16 v[194:195], v158 offset:0xe00
	s_waitcnt lgkmcnt(6)
	v_mfma_f32_32x32x16_bf16 v[48:63], v[176:179], v[180:183], v[48:63]
	ds_read_b64_tr_b16 v[180:181], v158 offset:0x1000
	ds_read_b64_tr_b16 v[182:183], v158 offset:0x1800
	v_mul_f32_e32 v114, 0xbe0293ee, v166
	v_max_f32_e32 v112, v65, v65
	v_max_f32_e32 v113, v64, v64
	v_fmamk_f32 v64, v64, 0x3e0293ee, v114
	v_max_f32_e32 v112, v113, v112
	v_exp_f32_e32 v64, v64
	s_waitcnt lgkmcnt(6)
	v_mfma_f32_32x32x16_bf16 v[32:47], v[176:179], v[184:187], v[32:47]
	ds_read_b64_tr_b16 v[184:185], v158 offset:0x1200
	ds_read_b64_tr_b16 v[186:187], v158 offset:0x1a00
	v_fmamk_f32 v65, v65, 0x3e0293ee, v114
	v_max3_f32 v112, v112, v66, v67
	v_exp_f32_e32 v65, v65
	v_fmamk_f32 v66, v66, 0x3e0293ee, v114
	v_exp_f32_e32 v66, v66
	s_waitcnt lgkmcnt(6)
	v_mfma_f32_32x32x16_bf16 v[16:31], v[176:179], v[188:191], v[16:31]
	ds_read_b64_tr_b16 v[188:189], v158 offset:0x1400
	ds_read_b64_tr_b16 v[190:191], v158 offset:0x1c00
	v_fmamk_f32 v67, v67, 0x3e0293ee, v114
	v_max3_f32 v112, v112, v68, v69
	v_exp_f32_e32 v67, v67
	v_fmamk_f32 v68, v68, 0x3e0293ee, v114
	v_add_f32_e32 v115, 0, v64
	s_waitcnt lgkmcnt(6)
	v_mfma_f32_32x32x16_bf16 v[0:15], v[176:179], v[192:195], v[0:15]
	ds_read_b64_tr_b16 v[192:193], v158 offset:0x1600
	ds_read_b64_tr_b16 v[194:195], v158 offset:0x1e00
	v_exp_f32_e32 v68, v68
	v_fmamk_f32 v69, v69, 0x3e0293ee, v114
	v_max3_f32 v112, v112, v70, v71
	v_add_f32_e32 v115, v65, v115
	v_exp_f32_e32 v69, v69
	s_waitcnt lgkmcnt(6)
	v_mfma_f32_32x32x16_bf16 v[48:63], v[124:127], v[180:183], v[48:63]
	ds_read_b64_tr_b16 v[180:181], v158 offset:0x2000
	ds_read_b64_tr_b16 v[182:183], v158 offset:0x2800
	v_fmamk_f32 v70, v70, 0x3e0293ee, v114
	v_add_f32_e32 v115, v66, v115
	v_exp_f32_e32 v70, v70
	v_fmamk_f32 v71, v71, 0x3e0293ee, v114
	v_max3_f32 v112, v112, v72, v73
	s_waitcnt lgkmcnt(6)
	v_mfma_f32_32x32x16_bf16 v[32:47], v[124:127], v[184:187], v[32:47]
	ds_read_b64_tr_b16 v[184:185], v158 offset:0x2200
	ds_read_b64_tr_b16 v[186:187], v158 offset:0x2a00
	v_add_f32_e32 v115, v67, v115
	v_exp_f32_e32 v71, v71
	v_fmamk_f32 v72, v72, 0x3e0293ee, v114
	v_add_f32_e32 v115, v68, v115
	v_exp_f32_e32 v72, v72
	s_waitcnt lgkmcnt(6)
	v_mfma_f32_32x32x16_bf16 v[16:31], v[124:127], v[188:191], v[16:31]
	ds_read_b64_tr_b16 v[188:189], v158 offset:0x2400
	ds_read_b64_tr_b16 v[190:191], v158 offset:0x2c00
	v_fmamk_f32 v73, v73, 0x3e0293ee, v114
	v_max3_f32 v112, v112, v74, v75
	v_add_f32_e32 v115, v69, v115
	v_exp_f32_e32 v73, v73
	v_fmamk_f32 v74, v74, 0x3e0293ee, v114
	s_waitcnt lgkmcnt(6)
	v_mfma_f32_32x32x16_bf16 v[0:15], v[124:127], v[192:195], v[0:15]
	ds_read_b64_tr_b16 v[192:193], v158 offset:0x2600
	ds_read_b64_tr_b16 v[194:195], v158 offset:0x2e00
	v_add_f32_e32 v115, v70, v115
	v_exp_f32_e32 v74, v74
	v_fmamk_f32 v75, v75, 0x3e0293ee, v114
	v_max3_f32 v112, v112, v76, v77
	v_add_f32_e32 v115, v71, v115
	s_waitcnt lgkmcnt(6)
	v_mfma_f32_32x32x16_bf16 v[48:63], v[172:175], v[180:183], v[48:63]
	ds_read_b64_tr_b16 v[180:181], v158 offset:0x3000
	ds_read_b64_tr_b16 v[182:183], v158 offset:0x3800
	v_exp_f32_e32 v75, v75
	v_fmamk_f32 v76, v76, 0x3e0293ee, v114
	v_add_f32_e32 v115, v72, v115
	v_exp_f32_e32 v76, v76
	v_fmamk_f32 v77, v77, 0x3e0293ee, v114
	s_waitcnt lgkmcnt(6)
	v_mfma_f32_32x32x16_bf16 v[32:47], v[172:175], v[184:187], v[32:47]
	ds_read_b64_tr_b16 v[184:185], v158 offset:0x3200
	ds_read_b64_tr_b16 v[186:187], v158 offset:0x3a00
	v_max3_f32 v112, v112, v78, v79
	v_add_f32_e32 v115, v73, v115
	v_exp_f32_e32 v77, v77
	v_fmamk_f32 v78, v78, 0x3e0293ee, v114
	v_add_f32_e32 v115, v74, v115
	s_waitcnt lgkmcnt(6)
	v_mfma_f32_32x32x16_bf16 v[16:31], v[172:175], v[188:191], v[16:31]
	ds_read_b64_tr_b16 v[188:189], v158 offset:0x3400
	ds_read_b64_tr_b16 v[190:191], v158 offset:0x3c00
	v_exp_f32_e32 v78, v78
	v_fmac_f32_e32 v114, 0x3e0293ee, v79
	v_add_f32_e32 v115, v75, v115
	v_exp_f32_e32 v79, v114
	v_add_f32_e32 v114, v76, v115
	s_waitcnt lgkmcnt(6)
	v_mfma_f32_32x32x16_bf16 v[0:15], v[172:175], v[192:195], v[0:15]
	ds_read_b64_tr_b16 v[192:193], v158 offset:0x3600
	ds_read_b64_tr_b16 v[194:195], v158 offset:0x3e00
	v_mov_b32_e32 v113, v112
	v_add_f32_e32 v114, v77, v114
	s_nop 0
	v_permlane32_swap_b32_e32 v112, v113
	v_add_f32_e32 v114, v78, v114
	v_add_f32_e32 v120, v79, v114
	v_max_f32_e32 v113, v113, v113
	s_waitcnt lgkmcnt(6)
	v_mfma_f32_32x32x16_bf16 v[48:63], v[168:171], v[180:183], v[48:63]
	v_max_f32_e32 v112, v112, v112
	v_max_f32_e32 v164, v112, v113
	v_mov_b32_e32 v121, v120
	v_cvt_pk_bf16_f32 v112, v64, v65
	v_cvt_pk_bf16_f32 v113, v66, v67
	v_cvt_pk_bf16_f32 v114, v68, v69
	v_cvt_pk_bf16_f32 v115, v70, v71
	s_waitcnt lgkmcnt(4)
	v_mfma_f32_32x32x16_bf16 v[32:47], v[168:171], v[184:187], v[32:47]
	v_cvt_pk_bf16_f32 v116, v72, v73
	v_cvt_pk_bf16_f32 v117, v74, v75
	v_cvt_pk_bf16_f32 v118, v76, v77
	v_cvt_pk_bf16_f32 v119, v78, v79
	s_nop 1
	v_permlane32_swap_b32_e32 v120, v121
	v_permlane32_swap_b32_e32 v112, v114
	s_waitcnt lgkmcnt(2)
	v_mfma_f32_32x32x16_bf16 v[16:31], v[168:171], v[188:191], v[16:31]
	v_permlane32_swap_b32_e32 v113, v115
	v_permlane32_swap_b32_e32 v116, v118
	v_permlane32_swap_b32_e32 v117, v119
	ds_write_b128 v157, v[112:115] offset:4096
	ds_write_b128 v157, v[116:119] offset:5120
	v_add_f32_e32 v120, v120, v121
	v_add_f32_e32 v155, v155, v120
	s_waitcnt lgkmcnt(2)
	v_mfma_f32_32x32x16_bf16 v[0:15], v[168:171], v[192:195], v[0:15]
	s_and_saveexec_b64 s[52:53], s[4:5]
	ds_write_b32 v160, v164 offset:8448
	s_or_b64 exec, exec, s[52:53]
	s_waitcnt vmcnt(0) lgkmcnt(0)
	s_barrier
	s_branch .LBB0_748

.Li1_entry:
	ds_read_b128 v[64:67], v148
	ds_read_b128 v[188:191], v150
	ds_read_b128 v[228:231], v152
	s_waitcnt lgkmcnt(2)
	v_mfma_f32_32x32x16_bf16 v[64:79], v[64:67], v[80:83], 0
	s_waitcnt lgkmcnt(1)
	v_mfma_f32_32x32x16_bf16 v[64:79], v[188:191], v[84:87], v[64:79]
	ds_read_b128 v[188:191], v154
	s_mov_b64 s[56:57], 0xe408000
	s_mov_b32 m0, s96
	v_lshl_add_u64 v[192:193], v[134:135], 0, s[56:57]
	global_load_lds_dwordx4 v[192:193], off
	v_cndmask_b32_e64 v173, v113, v121, s[2:3]
	v_cndmask_b32_e64 v172, v112, v120, s[2:3]
	v_cndmask_b32_e64 v177, v121, v113, s[2:3]
	v_cndmask_b32_e64 v176, v120, v112, s[2:3]
	s_waitcnt lgkmcnt(1)
	v_mfma_f32_32x32x16_bf16 v[64:79], v[228:231], v[88:91], v[64:79]
	ds_read_b128 v[228:231], v148 offset:128
	s_mov_b64 s[56:57], 0xe40a000
	s_mov_b32 m0, s6
	v_lshl_add_u64 v[192:193], v[134:135], 0, s[56:57]
	global_load_lds_dwordx4 v[192:193], off
	v_cndmask_b32_e64 v171, v127, v119, s[2:3]
	v_cndmask_b32_e64 v170, v126, v118, s[2:3]
	v_cndmask_b32_e64 v169, v125, v117, s[2:3]
	v_cndmask_b32_e64 v168, v124, v116, s[2:3]
	s_waitcnt lgkmcnt(1)
	v_mfma_f32_32x32x16_bf16 v[64:79], v[188:191], v[92:95], v[64:79]
	ds_read_b128 v[188:191], v150 offset:128
	s_mov_b64 s[56:57], 0xe808000
	s_mov_b32 m0, s7
	v_lshl_add_u64 v[192:193], v[134:135], 0, s[56:57]
	global_load_lds_dwordx4 v[192:193], off
	v_cndmask_b32_e64 v175, v115, v123, s[2:3]
	v_cndmask_b32_e64 v174, v114, v122, s[2:3]
	v_cndmask_b32_e64 v127, v119, v127, s[2:3]
	v_cndmask_b32_e64 v126, v118, v126, s[2:3]
	s_waitcnt lgkmcnt(1)
	v_mfma_f32_32x32x16_bf16 v[64:79], v[228:231], v[96:99], v[64:79]
	ds_read_b128 v[228:231], v152 offset:128
	s_mov_b64 s[56:57], 0xe80a000
	s_mov_b32 m0, s24
	v_lshl_add_u64 v[192:193], v[134:135], 0, s[56:57]
	global_load_lds_dwordx4 v[192:193], off
	v_cndmask_b32_e64 v125, v117, v125, s[2:3]
	v_cndmask_b32_e64 v124, v116, v124, s[2:3]
	v_cndmask_b32_e64 v179, v123, v115, s[2:3]
	v_cndmask_b32_e64 v178, v122, v114, s[2:3]
	s_waitcnt lgkmcnt(1)
	v_mfma_f32_32x32x16_bf16 v[64:79], v[188:191], v[100:103], v[64:79]
	ds_read_b128 v[188:191], v154 offset:128
	s_add_i32 s56, s19, 1
	s_cmp_gt_i32 s56, s18
	s_cbranch_scc1 .Li1_kskip
	v_lshl_add_u64 v[192:193], s[50:51], 0, v[130:131]
	s_mov_b64 s[56:57], 0xc40c000
	s_mov_b32 m0, s27
	v_lshl_add_u64 v[192:193], v[192:193], 0, s[56:57]
	global_load_lds_dwordx4 v[192:193], off
	v_lshl_add_u64 v[192:193], s[50:51], 0, v[130:131]
	s_mov_b64 s[56:57], 0xc40e000
	s_mov_b32 m0, s62
	v_lshl_add_u64 v[192:193], v[192:193], 0, s[56:57]
	global_load_lds_dwordx4 v[192:193], off

.Li1_sm:
	ds_read_b64_tr_b16 v[188:189], v158 offset:0x8400
	ds_read_b64_tr_b16 v[190:191], v158 offset:0x8c00
	ds_read_b64_tr_b16 v[192:193], v158 offset:0x8600
	ds_read_b64_tr_b16 v[194:195], v158 offset:0x8e00
	s_waitcnt lgkmcnt(6)
	v_mfma_f32_32x32x16_bf16 v[48:63], v[176:179], v[180:183], v[48:63]
	ds_read_b64_tr_b16 v[180:181], v158 offset:0x9000
	ds_read_b64_tr_b16 v[182:183], v158 offset:0x9800
	v_mul_f32_e32 v114, 0xbe0293ee, v165
	v_max_f32_e32 v112, v65, v65
	v_max_f32_e32 v113, v64, v64
	v_fmamk_f32 v64, v64, 0x3e0293ee, v114
	v_max_f32_e32 v112, v113, v112
	v_exp_f32_e32 v64, v64
	s_waitcnt lgkmcnt(6)
	v_mfma_f32_32x32x16_bf16 v[32:47], v[176:179], v[184:187], v[32:47]
	ds_read_b64_tr_b16 v[184:185], v158 offset:0x9200
	ds_read_b64_tr_b16 v[186:187], v158 offset:0x9a00
	v_fmamk_f32 v65, v65, 0x3e0293ee, v114
	v_max3_f32 v112, v112, v66, v67
	v_exp_f32_e32 v65, v65
	v_fmamk_f32 v66, v66, 0x3e0293ee, v114
	v_exp_f32_e32 v66, v66
	s_waitcnt lgkmcnt(6)
	v_mfma_f32_32x32x16_bf16 v[16:31], v[176:179], v[188:191], v[16:31]
	ds_read_b64_tr_b16 v[188:189], v158 offset:0x9400
	ds_read_b64_tr_b16 v[190:191], v158 offset:0x9c00
	v_fmamk_f32 v67, v67, 0x3e0293ee, v114
	v_max3_f32 v112, v112, v68, v69
	v_exp_f32_e32 v67, v67
	v_fmamk_f32 v68, v68, 0x3e0293ee, v114
	v_add_f32_e32 v115, 0, v64
	s_waitcnt lgkmcnt(6)
	v_mfma_f32_32x32x16_bf16 v[0:15], v[176:179], v[192:195], v[0:15]
	ds_read_b64_tr_b16 v[192:193], v158 offset:0x9600
	ds_read_b64_tr_b16 v[194:195], v158 offset:0x9e00
	v_exp_f32_e32 v68, v68
	v_fmamk_f32 v69, v69, 0x3e0293ee, v114
	v_max3_f32 v112, v112, v70, v71
	v_add_f32_e32 v115, v65, v115
	v_exp_f32_e32 v69, v69
	s_waitcnt lgkmcnt(6)
	v_mfma_f32_32x32x16_bf16 v[48:63], v[168:171], v[180:183], v[48:63]
	ds_read_b64_tr_b16 v[180:181], v158 offset:0xa000
	ds_read_b64_tr_b16 v[182:183], v158 offset:0xa800
	v_fmamk_f32 v70, v70, 0x3e0293ee, v114
	v_add_f32_e32 v115, v66, v115
	v_exp_f32_e32 v70, v70
	v_fmamk_f32 v71, v71, 0x3e0293ee, v114
	v_max3_f32 v112, v112, v72, v73
	s_waitcnt lgkmcnt(6)
	v_mfma_f32_32x32x16_bf16 v[32:47], v[168:171], v[184:187], v[32:47]
	ds_read_b64_tr_b16 v[184:185], v158 offset:0xa200
	ds_read_b64_tr_b16 v[186:187], v158 offset:0xaa00
	v_add_f32_e32 v115, v67, v115
	v_exp_f32_e32 v71, v71
	v_fmamk_f32 v72, v72, 0x3e0293ee, v114
	v_add_f32_e32 v115, v68, v115
	v_exp_f32_e32 v72, v72
	s_waitcnt lgkmcnt(6)
	v_mfma_f32_32x32x16_bf16 v[16:31], v[168:171], v[188:191], v[16:31]
	ds_read_b64_tr_b16 v[188:189], v158 offset:0xa400
	ds_read_b64_tr_b16 v[190:191], v158 offset:0xac00
	v_fmamk_f32 v73, v73, 0x3e0293ee, v114
	v_max3_f32 v112, v112, v74, v75
	v_add_f32_e32 v115, v69, v115
	v_exp_f32_e32 v73, v73
	v_fmamk_f32 v74, v74, 0x3e0293ee, v114
	s_waitcnt lgkmcnt(6)
	v_mfma_f32_32x32x16_bf16 v[0:15], v[168:171], v[192:195], v[0:15]
	ds_read_b64_tr_b16 v[192:193], v158 offset:0xa600
	ds_read_b64_tr_b16 v[194:195], v158 offset:0xae00
	v_add_f32_e32 v115, v70, v115
	v_exp_f32_e32 v74, v74
	v_fmamk_f32 v75, v75, 0x3e0293ee, v114
	v_max3_f32 v112, v112, v76, v77
	v_add_f32_e32 v115, v71, v115
	s_waitcnt lgkmcnt(6)
	v_mfma_f32_32x32x16_bf16 v[48:63], v[172:175], v[180:183], v[48:63]
	ds_read_b64_tr_b16 v[180:181], v158 offset:0xb000
	ds_read_b64_tr_b16 v[182:183], v158 offset:0xb800
	v_exp_f32_e32 v75, v75
	v_fmamk_f32 v76, v76, 0x3e0293ee, v114
	v_add_f32_e32 v115, v72, v115
	v_exp_f32_e32 v76, v76
	v_fmamk_f32 v77, v77, 0x3e0293ee, v114
	s_waitcnt lgkmcnt(6)
	v_mfma_f32_32x32x16_bf16 v[32:47], v[172:175], v[184:187], v[32:47]
	ds_read_b64_tr_b16 v[184:185], v158 offset:0xb200
	ds_read_b64_tr_b16 v[186:187], v158 offset:0xba00
	v_max3_f32 v112, v112, v78, v79
	v_add_f32_e32 v115, v73, v115
	v_exp_f32_e32 v77, v77
	v_fmamk_f32 v78, v78, 0x3e0293ee, v114
	v_add_f32_e32 v115, v74, v115
	s_waitcnt lgkmcnt(6)
	v_mfma_f32_32x32x16_bf16 v[16:31], v[172:175], v[188:191], v[16:31]
	ds_read_b64_tr_b16 v[188:189], v158 offset:0xb400
	ds_read_b64_tr_b16 v[190:191], v158 offset:0xbc00
	v_exp_f32_e32 v78, v78
	v_fmac_f32_e32 v114, 0x3e0293ee, v79
	v_add_f32_e32 v115, v75, v115
	v_exp_f32_e32 v79, v114
	v_add_f32_e32 v114, v76, v115
	s_waitcnt lgkmcnt(6)
	v_mfma_f32_32x32x16_bf16 v[0:15], v[172:175], v[192:195], v[0:15]
	ds_read_b64_tr_b16 v[192:193], v158 offset:0xb600
	ds_read_b64_tr_b16 v[194:195], v158 offset:0xbe00
	v_mov_b32_e32 v113, v112
	v_add_f32_e32 v114, v77, v114
	s_nop 0
	v_permlane32_swap_b32_e32 v112, v113
	v_add_f32_e32 v114, v78, v114
	v_add_f32_e32 v120, v79, v114
	v_max_f32_e32 v113, v113, v113
	s_waitcnt lgkmcnt(6)
	v_mfma_f32_32x32x16_bf16 v[48:63], v[124:127], v[180:183], v[48:63]
	v_max_f32_e32 v112, v112, v112
	v_max_f32_e32 v164, v112, v113
	v_mov_b32_e32 v121, v120
	v_cvt_pk_bf16_f32 v112, v64, v65
	v_cvt_pk_bf16_f32 v113, v66, v67
	v_cvt_pk_bf16_f32 v114, v68, v69
	v_cvt_pk_bf16_f32 v115, v70, v71
	s_waitcnt lgkmcnt(4)
	v_mfma_f32_32x32x16_bf16 v[32:47], v[124:127], v[184:187], v[32:47]
	v_cvt_pk_bf16_f32 v116, v72, v73
	v_cvt_pk_bf16_f32 v117, v74, v75
	v_cvt_pk_bf16_f32 v118, v76, v77
	v_cvt_pk_bf16_f32 v119, v78, v79
	s_nop 1
	v_permlane32_swap_b32_e32 v120, v121
	v_permlane32_swap_b32_e32 v112, v114
	s_waitcnt lgkmcnt(2)
	v_mfma_f32_32x32x16_bf16 v[16:31], v[124:127], v[188:191], v[16:31]
	v_permlane32_swap_b32_e32 v113, v115
	v_permlane32_swap_b32_e32 v116, v118
	v_permlane32_swap_b32_e32 v117, v119
	ds_write_b128 v157, v[112:115]
	ds_write_b128 v157, v[116:119] offset:1024
	v_add_f32_e32 v120, v120, v121
	v_add_f32_e32 v155, v155, v120
	s_waitcnt lgkmcnt(2)
	v_mfma_f32_32x32x16_bf16 v[0:15], v[124:127], v[192:195], v[0:15]
	s_and_saveexec_b64 s[54:55], s[4:5]
	ds_write_b32 v160, v164 offset:8192
	s_or_b64 exec, exec, s[54:55]
	s_waitcnt vmcnt(0) lgkmcnt(0)
	s_barrier
	s_branch .LBB0_733
